# stacked: v26 + DPP shuffles + dead-copy skip on single-active paths + P3 rope-k load hoist + static prio waves 4-7 in attention + 64B-aligned loop heads
# speedup vs baseline: 1.0103x; 1.0043x over previous
; __device__ __forceinline__ float af_sigmoid(float x) { return 1.f / (1.f + __expf(-x)); }
; __device__ __forceinline__ void attn_fast(const Ptrs& P, LAS unsigned char* lds, int G, int bid) {
;     ...
;                 const int j_lo = br == 1 ? 0 : (qb >= 8 ? qb - 8 : 0);
;                 const int nt = qb - j_lo + 1;
;                 m[0] = m[1] = -1.0e30f; l[0] = l[1] = 0.f;
; #pragma unroll
;                 for (int ct = 0; ct < 2; ++ct)
; #pragma unroll
;                     for (int dt = 0; dt < 8; ++dt) o[ct][dt] = (f32x4){0.f, 0.f, 0.f, 0.f};
;                 AF_ISSUE(0, KB, VB, DINP, 64 * j_lo, true);
;                 if (nt > 1) AF_ISSUE(1, KB, VB, DINP, 64 * (j_lo + 1), true);
;                 if (nt > 2) AF_ISSUE(2, KB, VB, DINP, 64 * (j_lo + 2), true);
;     ...
;                 for (int ct = 0; ct < 2; ++ct) { int _ln; asm volatile("v_mov_b32 %0, %1" : "=v"(_ln) : "v"(lane));
;                     const int fr_ = _ln & 15, fq_ = _ln >> 4, hh_ = fr_ & 3;
;                     const size_t row = (size_t)b * SEQ + 64 * qb + 8 * w + 4 * ct + (fr_ >> 2);
;                     float lt = l[ct]; lt += __shfl_xor(lt, 16); lt += __shfl_xor(lt, 32);
;                     const float gg = af_sigmoid((float)U[row * DINP + OFF_GL + (4 * g + hh_) * 3 + br]);
.LBB0_578:
.LBB0_580:
	s_cmp_lt_i32 s17, 0
	s_cbranch_scc1 .LBB0_622
	v_lshrrev_b32_e32 v38, 2, v172
	v_and_or_b32 v42, v38, 3, s28
	v_and_or_b32 v38, v38, 3, s37
	v_and_or_b32 v40, v172, 3, s1
	v_mul_u32_u24_e32 v40, 3, v40
	v_lshlrev_b32_e32 v40, 1, v40
	v_mov_b32_e32 v41, 0
	v_mov_b32_e32 v39, s95
	v_mov_b64_e32 v[44:45], s[18:19]
	v_mad_u64_u32 v[44:45], s[8:9], v38, s86, v[44:45]
	v_mov_b32_e32 v2, v45
	v_mad_u64_u32 v[46:47], s[8:9], v39, s86, v[2:3]
	v_mov_b32_e32 v45, v46
	v_lshl_add_u64 v[44:45], v[44:45], 0, v[40:41]
	v_lshl_add_u64 v[44:45], s[52:53], 1, v[44:45]
	v_add_co_u32_e32 v44, vcc, s93, v44
	s_nop 1
	v_addc_co_u32_e32 v45, vcc, 0, v45, vcc
	global_load_ushort v254, v[44:45], off offset:3072
	v_mov_b64_e32 v[44:45], s[18:19]
	v_mad_u64_u32 v[44:45], s[8:9], v42, s86, v[44:45]
	v_mov_b32_e32 v2, v45
	v_mad_u64_u32 v[46:47], s[8:9], v39, s86, v[2:3]
	v_mov_b32_e32 v45, v46
	v_lshl_add_u64 v[44:45], v[44:45], 0, v[40:41]
	v_lshl_add_u64 v[44:45], s[52:53], 1, v[44:45]
	v_add_co_u32_e32 v44, vcc, s93, v44
	s_nop 1
	v_addc_co_u32_e32 v45, vcc, 0, v45, vcc
	global_load_ushort v255, v[44:45], off offset:3072
	v_mov_b32_e32 v4, v3
	v_mov_b32_e32 v5, v3
	v_mov_b32_e32 v2, v3
	v_mov_b64_e32 v[40:41], v[4:5]
	v_mov_b64_e32 v[44:45], v[4:5]
	v_mov_b64_e32 v[56:57], v[4:5]
	v_mov_b64_e32 v[60:61], v[4:5]
	v_mov_b64_e32 v[72:73], v[4:5]
	v_mov_b64_e32 v[80:81], v[4:5]
	v_mov_b64_e32 v[92:93], v[4:5]
	v_mov_b64_e32 v[100:101], v[4:5]
	v_mov_b64_e32 v[96:97], v[4:5]
	v_mov_b64_e32 v[88:89], v[4:5]
	v_mov_b64_e32 v[84:85], v[4:5]
	v_mov_b64_e32 v[76:77], v[4:5]
	v_mov_b64_e32 v[68:69], v[4:5]
	v_mov_b64_e32 v[64:65], v[4:5]
	v_mov_b64_e32 v[52:53], v[4:5]
	v_mov_b64_e32 v[48:49], v[4:5]
	s_add_i32 s22, s17, 1
	s_mov_b32 s23, 0
	v_mov_b32_e32 v217, 0xf149f2ca
	v_mov_b32_e32 v216, 0
	v_mov_b64_e32 v[38:39], v[2:3]
	v_mov_b64_e32 v[42:43], v[2:3]
	v_mov_b64_e32 v[54:55], v[2:3]
	v_mov_b64_e32 v[58:59], v[2:3]
	v_mov_b64_e32 v[70:71], v[2:3]
	v_mov_b64_e32 v[78:79], v[2:3]
	v_mov_b64_e32 v[90:91], v[2:3]
	v_mov_b64_e32 v[98:99], v[2:3]
	v_mov_b64_e32 v[94:95], v[2:3]
	v_mov_b64_e32 v[86:87], v[2:3]
	v_mov_b64_e32 v[82:83], v[2:3]
	v_mov_b64_e32 v[74:75], v[2:3]
	v_mov_b64_e32 v[66:67], v[2:3]
	v_mov_b64_e32 v[62:63], v[2:3]
	v_mov_b64_e32 v[50:51], v[2:3]
	v_mov_b64_e32 v[46:47], v[2:3]
	v_mov_b32_e32 v5, 0
	v_mov_b32_e32 v4, 0xf149f2ca
	s_mov_b32 s3, 0
	.p2alignl 6, 3212836864

; #define LAS __attribute__((address_space(3)))
; #define AF_WAITV(n) asm volatile("s_waitcnt vmcnt(" #n ")" ::: "memory")
; #define AF_BAR() do { __builtin_amdgcn_s_barrier(); asm volatile("" ::: "memory"); } while (0)
; __device__ __forceinline__ void attn_fast(const Ptrs& P, LAS unsigned char* lds, int G, int bid) {
;     ...
;                 for (int i = 0; i < nt; ++i) {
;                     const int j = j_lo + i;
;                     if (i + 2 < nt) AF_WAITV(8); else if (i + 1 < nt) AF_WAITV(4); else AF_WAITV(0);
;                     AF_BAR();
;                     if (i + 3 < nt) AF_ISSUE((i + 3) & 3, KB, VB, DINP, 64 * (j + 3), true);
;                     int hi[2], lo[2]; bool act[2];
;                     const bool needmask = (j == qb) || (br == 2 && 64 * j <= 64 * qb + 63 - 512);
; #pragma unroll
;                     for (int ct = 0; ct < 2; ++ct) {
;                         if (br == 1) { const unsigned wd = SELM[(8 * w + 4 * ct + qi) * 4 + (j >> 5)]; const bool bit = (wd >> (j & 31)) & 1u;
;                             act[ct] = __ballot(bit) != 0ull; hi[ct] = bit ? tq[ct] : -1; lo[ct] = NEGBIG; }
;                         else { act[ct] = true; hi[ct] = tq[ct]; lo[ct] = tq[ct] - 512; }
;                     }
;                     const LAS unsigned char* stg = lds + (i & 3) * 32768;
;                     if (act[0] && act[1]) af_tile_online<true, true>(stg, kl, vl0, vz, qf, s, m, l, o, needmask, 64 * j, fq, hi, lo, SC);
;                     else if (act[0])      af_tile_online<true, false>(stg, kl, vl0, vz, qf, s, m, l, o, needmask, 64 * j, fq, hi, lo, SC);
;                     else if (act[1])      af_tile_online<false, true>(stg, kl, vl0, vz, qf, s, m, l, o, needmask, 64 * j, fq, hi, lo, SC);
;                 }
.LBB0_621:
	v_mov_b32_e32 v221, v217
	s_and_b64 vcc, exec, s[8:9]
	s_cbranch_vccz .LBB0_615
	s_branch .LBB0_616
	.p2alignl 6, 3212836864
